# c11 plus removal of dead store-address arithmetic (85 VALU lines) in the gating epilogue after its stores moved to LDS staging
# baseline (speedup 1.0000x reference)
; __device__ __forceinline__ float bf2f(unsigned short h) { return __uint_as_float(((unsigned)h) << 16); }
; __device__ __forceinline__ unsigned cvtpk(float lo, float hi) { unsigned r; asm volatile("v_cvt_pk_bf16_f32 %0, %1, %2" : "=v"(r) : "v"(lo), "v"(hi)); return r; }
; __device__ __forceinline__ int crow(int r, int hi) { return (r & 3) + 8 * (r >> 2) + 4 * hi; }
; __device__ __forceinline__ void ph_misc(const Args& a, char* lds, int l) {
;     ...
;         for (int ci = 0; ci < 2; ++ci)
; #pragma unroll
;             for (int r = 0; r < 16; ++r) { const int t = 32 * tb + crow(r, hi), c = 32 * (cb0 + ci) + r32; const size_t row = row0 + t;
;                 const float uval = gelu_tanh(bf2f(P[row * NIN + PC_U + g * 128 + c])); const float val = uval * (acc[ci][r] + b_s[l * 512 + g * 128 + t]);
;                 const float vn = __shfl_xor(val, 1); if ((r32 & 1) == 0) *(unsigned*)(MIX + row * DM + 1024 + g * 128 + c) = cvtpk(val, vn); }
.LBB0_672:
	s_lshl_b64 s[0:1], s[34:35], 7
	v_or_b32_e32 v72, s0, v36
	v_mov_b64_e32 v[74:75], s[16:17]
	v_mad_u64_u32 v[74:75], s[6:7], v72, s83, v[74:75]
	v_mad_i32_i24 v75, s1, v244, v75
	s_lshl_b32 s86, s2, 1
	v_lshl_add_u64 v[74:75], v[74:75], 0, s[86:87]
	v_lshl_add_u64 v[74:75], v[38:39], 1, v[74:75]
	v_and_b32_e32 v200, 31, v243
	v_lshrrev_b32_e32 v201, 5, v243
	v_lshlrev_b32_e32 v202, 2, v201
	v_sub_u32_e32 v203, v36, v202
	v_add_u32_e32 v203, v203, v200
	v_or_b32_e32 v203, s0, v203
	v_mov_b64_e32 v[204:205], s[16:17]
	v_mad_u64_u32 v[204:205], s[6:7], v203, s83, v[204:205]
	v_mad_i32_i24 v205, s1, v244, v205
	v_lshl_add_u64 v[204:205], v[204:205], 0, s[86:87]
	v_lshl_add_u64 v[204:205], v[38:39], 1, v[204:205]
	v_lshlrev_b32_e32 v206, 6, v201
	v_add_co_u32_e32 v204, vcc, v204, v206
	s_nop 1
	v_addc_co_u32_e32 v205, vcc, 0, v205, vcc
	v_add_co_u32_e32 v204, vcc, 0x1000, v204
	s_nop 1
	v_addc_co_u32_e32 v205, vcc, 0, v205, vcc
	global_load_dword v207, v[204:205], off offset:512
	v_and_b32_e32 v208, 0xffffffc0, v240
	v_lshlrev_b32_e32 v208, 6, v208
	v_lshl_add_u32 v208, v201, 9, v208
	v_lshl_add_u32 v208, v200, 1, v208
	v_add_u32_e32 v208, 0xa000, v208
	s_movk_i32 s2, 0x1000
	v_add_co_u32_e32 v76, vcc, s2, v74
	v_or_b32_e32 v0, s38, v36
	s_nop 0
	v_addc_co_u32_e32 v77, vcc, 0, v75, vcc
	flat_load_ushort v61, v[76:77] offset:512
	v_lshl_add_u64 v[78:79], v[0:1], 2, s[14:15]
	flat_load_dword v0, v[78:79]
	v_mov_b32_e32 v73, s1
	v_lshlrev_b64 v[72:73], 12, v[72:73]
	v_lshl_add_u64 v[76:77], s[22:23], 0, v[72:73]
	s_waitcnt vmcnt(0) lgkmcnt(0)
	v_lshlrev_b32_e32 v61, 16, v61
	v_mul_f32_e32 v63, 0x3d372713, v61
	v_mul_f32_e32 v63, v63, v61
	v_fma_f32 v63, v63, v61, v61
	v_mul_f32_e32 v63, 0x3f4c422a, v63
	v_mul_f32_e32 v63, 0xc038aa3b, v63
	v_exp_f32_e32 v63, v63
	v_add_f32_e32 v0, v18, v0
	v_add_f32_e32 v63, 1.0, v63
	v_rcp_f32_e32 v63, v63
	s_nop 0
	v_mul_f32_e32 v61, v63, v61
	v_mul_f32_e32 v0, v0, v61
	s_nop 1
	v_mov_b32_dpp v18, v0 quad_perm:[1,0,3,2] row_mask:0xf bank_mask:0xf
	s_and_saveexec_b64 s[6:7], s[4:5]
	s_cbranch_execz .LBB0_674
	s_waitcnt lgkmcnt(0)
	v_cvt_pk_bf16_f32 v0, v0, v18
	ds_write_b32 v208, v0 offset:0
.LBB0_674:
	s_or_b64 exec, exec, s[6:7]
	s_waitcnt lgkmcnt(0)
	v_or_b32_e32 v18, s0, v40
	v_mov_b64_e32 v[72:73], s[16:17]
	v_mad_u64_u32 v[72:73], s[6:7], v18, s83, v[72:73]
	v_mad_i32_i24 v73, s1, v244, v73
	v_lshl_add_u64 v[72:73], v[72:73], 0, s[86:87]
	v_lshl_add_u64 v[80:81], v[38:39], 1, v[72:73]
	v_add_co_u32_e32 v72, vcc, s2, v80
	v_add_u32_e32 v0, s38, v36
	s_nop 0
	v_addc_co_u32_e32 v73, vcc, 0, v81, vcc
	flat_load_ushort v61, v[72:73] offset:512
	v_lshl_add_u64 v[72:73], v[0:1], 2, s[14:15]
	flat_load_dword v0, v[72:73] offset:4
	s_waitcnt vmcnt(0) lgkmcnt(0)
	v_lshlrev_b32_e32 v61, 16, v61
	v_mul_f32_e32 v63, 0x3d372713, v61
	v_mul_f32_e32 v63, v63, v61
	v_fma_f32 v63, v63, v61, v61
	v_mul_f32_e32 v63, 0x3f4c422a, v63
	v_mul_f32_e32 v63, 0xc038aa3b, v63
	v_exp_f32_e32 v63, v63
	v_add_f32_e32 v0, v19, v0
	v_mov_b32_e32 v19, s1
	v_lshlrev_b64 v[18:19], 12, v[18:19]
	v_add_f32_e32 v63, 1.0, v63
	v_rcp_f32_e32 v63, v63
	v_lshl_add_u64 v[18:19], s[22:23], 0, v[18:19]
	v_mul_f32_e32 v61, v63, v61
	v_mul_f32_e32 v0, v0, v61
	s_nop 1
	v_mov_b32_dpp v61, v0 quad_perm:[1,0,3,2] row_mask:0xf bank_mask:0xf
	s_and_saveexec_b64 s[6:7], s[4:5]
	s_cbranch_execz .LBB0_676
	s_waitcnt lgkmcnt(0)
	v_cvt_pk_bf16_f32 v0, v0, v61
	ds_write_b32 v208, v0 offset:128
.LBB0_676:
	s_or_b64 exec, exec, s[6:7]
	v_or_b32_e32 v84, s0, v42
	v_mov_b64_e32 v[82:83], s[16:17]
	v_mad_u64_u32 v[82:83], s[6:7], v84, s83, v[82:83]
	v_mad_i32_i24 v83, s1, v244, v83
	v_lshl_add_u64 v[82:83], v[82:83], 0, s[86:87]
	v_lshl_add_u64 v[82:83], v[38:39], 1, v[82:83]
	v_add_co_u32_e32 v86, vcc, s2, v82
	v_mov_b32_e32 v85, s1
	s_nop 0
	v_addc_co_u32_e32 v87, vcc, 0, v83, vcc
	flat_load_ushort v0, v[86:87] offset:512
	s_waitcnt lgkmcnt(0)
	flat_load_dword v61, v[72:73] offset:8
	v_lshlrev_b64 v[84:85], 12, v[84:85]
	v_lshl_add_u64 v[84:85], s[22:23], 0, v[84:85]
	s_waitcnt vmcnt(0)
	v_lshlrev_b32_e32 v0, 16, v0
	v_mul_f32_e32 v63, 0x3d372713, v0
	v_mul_f32_e32 v63, v63, v0
	v_fma_f32 v63, v63, v0, v0
	v_mul_f32_e32 v63, 0x3f4c422a, v63
	v_mul_f32_e32 v63, 0xc038aa3b, v63
	v_exp_f32_e32 v63, v63
	s_waitcnt lgkmcnt(0)
	v_add_f32_e32 v20, v20, v61
	v_add_f32_e32 v63, 1.0, v63
	v_rcp_f32_e32 v63, v63
	s_nop 0
	v_mul_f32_e32 v0, v63, v0
	v_mul_f32_e32 v0, v20, v0
	s_nop 1
	v_mov_b32_dpp v20, v0 quad_perm:[1,0,3,2] row_mask:0xf bank_mask:0xf
	s_and_saveexec_b64 s[6:7], s[4:5]
	s_cbranch_execz .LBB0_678
	s_waitcnt lgkmcnt(0)
	v_cvt_pk_bf16_f32 v0, v0, v20
	ds_write_b32 v208, v0 offset:256
.LBB0_678:
	s_or_b64 exec, exec, s[6:7]
	s_waitcnt lgkmcnt(0)
	v_or_b32_e32 v20, s0, v44
	v_mov_b64_e32 v[86:87], s[16:17]
	v_mad_u64_u32 v[86:87], s[6:7], v20, s83, v[86:87]
	v_mad_i32_i24 v87, s1, v244, v87
	v_lshl_add_u64 v[86:87], v[86:87], 0, s[86:87]
	v_lshl_add_u64 v[86:87], v[38:39], 1, v[86:87]
	v_add_co_u32_e32 v88, vcc, s2, v86
	s_nop 1
	v_addc_co_u32_e32 v89, vcc, 0, v87, vcc
	flat_load_ushort v0, v[88:89] offset:512
	flat_load_dword v61, v[72:73] offset:12
	s_waitcnt vmcnt(0) lgkmcnt(0)
	v_lshlrev_b32_e32 v0, 16, v0
	v_mul_f32_e32 v63, 0x3d372713, v0
	v_mul_f32_e32 v63, v63, v0
	v_fma_f32 v63, v63, v0, v0
	v_mul_f32_e32 v63, 0x3f4c422a, v63
	v_mul_f32_e32 v63, 0xc038aa3b, v63
	v_exp_f32_e32 v63, v63
	v_add_f32_e32 v21, v21, v61
	v_add_f32_e32 v63, 1.0, v63
	v_rcp_f32_e32 v63, v63
	s_nop 0
	v_mul_f32_e32 v0, v63, v0
	v_mul_f32_e32 v0, v21, v0
	ds_bpermute_b32 v61, v43, v0
	v_mov_b32_e32 v21, s1
	v_lshlrev_b64 v[20:21], 12, v[20:21]
	v_lshl_add_u64 v[20:21], s[22:23], 0, v[20:21]
	s_and_saveexec_b64 s[6:7], s[4:5]
	s_cbranch_execz .LBB0_680
	s_waitcnt lgkmcnt(0)
	v_cvt_pk_bf16_f32 v0, v0, v61
	ds_write_b32 v208, v0 offset:384
; __device__ __forceinline__ float bf2f(unsigned short h) { return __uint_as_float(((unsigned)h) << 16); }
; __device__ __forceinline__ unsigned cvtpk(float lo, float hi) { unsigned r; asm volatile("v_cvt_pk_bf16_f32 %0, %1, %2" : "=v"(r) : "v"(lo), "v"(hi)); return r; }
; __device__ __forceinline__ int crow(int r, int hi) { return (r & 3) + 8 * (r >> 2) + 4 * hi; }
; __device__ __forceinline__ void ph_misc(const Args& a, char* lds, int l) {
;     ...
;         for (int ci = 0; ci < 2; ++ci)
; #pragma unroll
;             for (int r = 0; r < 16; ++r) { const int t = 32 * tb + crow(r, hi), c = 32 * (cb0 + ci) + r32; const size_t row = row0 + t;
;                 const float uval = gelu_tanh(bf2f(P[row * NIN + PC_U + g * 128 + c])); const float val = uval * (acc[ci][r] + b_s[l * 512 + g * 128 + t]);
;                 const float vn = __shfl_xor(val, 1); if ((r32 & 1) == 0) *(unsigned*)(MIX + row * DM + 1024 + g * 128 + c) = cvtpk(val, vn); }
.LBB0_680:
	s_or_b64 exec, exec, s[6:7]
	v_or_b32_e32 v90, s0, v46
	v_mov_b64_e32 v[88:89], s[16:17]
	v_mad_u64_u32 v[88:89], s[6:7], v90, s83, v[88:89]
	v_mad_i32_i24 v89, s1, v244, v89
	v_lshl_add_u64 v[88:89], v[88:89], 0, s[86:87]
	v_lshl_add_u64 v[88:89], v[38:39], 1, v[88:89]
	v_add_co_u32_e32 v92, vcc, s2, v88
	v_mov_b32_e32 v91, s1
	s_nop 0
	v_addc_co_u32_e32 v93, vcc, 0, v89, vcc
	flat_load_ushort v0, v[92:93] offset:512
	s_waitcnt lgkmcnt(0)
	flat_load_dword v61, v[72:73] offset:32
	v_lshlrev_b64 v[90:91], 12, v[90:91]
	v_lshl_add_u64 v[90:91], s[22:23], 0, v[90:91]
	s_waitcnt vmcnt(0)
	v_lshlrev_b32_e32 v0, 16, v0
	v_mul_f32_e32 v63, 0x3d372713, v0
	v_mul_f32_e32 v63, v63, v0
	v_fma_f32 v63, v63, v0, v0
	v_mul_f32_e32 v63, 0x3f4c422a, v63
	v_mul_f32_e32 v63, 0xc038aa3b, v63
	v_exp_f32_e32 v63, v63
	s_waitcnt lgkmcnt(0)
	v_add_f32_e32 v22, v22, v61
	v_add_f32_e32 v63, 1.0, v63
	v_rcp_f32_e32 v63, v63
	s_nop 0
	v_mul_f32_e32 v0, v63, v0
	v_mul_f32_e32 v0, v22, v0
	s_nop 1
	v_mov_b32_dpp v22, v0 quad_perm:[1,0,3,2] row_mask:0xf bank_mask:0xf
	s_and_saveexec_b64 s[6:7], s[4:5]
	s_cbranch_execz .LBB0_682
	s_waitcnt lgkmcnt(0)
	v_cvt_pk_bf16_f32 v0, v0, v22
	ds_write_b32 v208, v0 offset:1024
.LBB0_682:
	s_or_b64 exec, exec, s[6:7]
	s_waitcnt lgkmcnt(0)
	v_or_b32_e32 v22, s0, v48
	v_mov_b64_e32 v[92:93], s[16:17]
	v_mad_u64_u32 v[92:93], s[6:7], v22, s83, v[92:93]
	v_mad_i32_i24 v93, s1, v244, v93
	v_lshl_add_u64 v[92:93], v[92:93], 0, s[86:87]
	v_lshl_add_u64 v[92:93], v[38:39], 1, v[92:93]
	v_add_co_u32_e32 v94, vcc, s2, v92
	s_nop 1
	v_addc_co_u32_e32 v95, vcc, 0, v93, vcc
	flat_load_ushort v0, v[94:95] offset:512
	flat_load_dword v61, v[72:73] offset:36
	s_waitcnt vmcnt(0) lgkmcnt(0)
	v_lshlrev_b32_e32 v0, 16, v0
	v_mul_f32_e32 v63, 0x3d372713, v0
	v_mul_f32_e32 v63, v63, v0
	v_fma_f32 v63, v63, v0, v0
	v_mul_f32_e32 v63, 0x3f4c422a, v63
	v_mul_f32_e32 v63, 0xc038aa3b, v63
	v_exp_f32_e32 v63, v63
	v_add_f32_e32 v23, v23, v61
	v_add_f32_e32 v63, 1.0, v63
	v_rcp_f32_e32 v63, v63
	s_nop 0
	v_mul_f32_e32 v0, v63, v0
	v_mul_f32_e32 v0, v23, v0
	ds_bpermute_b32 v61, v43, v0
	v_mov_b32_e32 v23, s1
	v_lshlrev_b64 v[22:23], 12, v[22:23]
	v_lshl_add_u64 v[22:23], s[22:23], 0, v[22:23]
	s_and_saveexec_b64 s[6:7], s[4:5]
	s_cbranch_execz .LBB0_684
	s_waitcnt lgkmcnt(0)
	v_cvt_pk_bf16_f32 v0, v0, v61
	ds_write_b32 v208, v0 offset:1152
.LBB0_684:
	s_or_b64 exec, exec, s[6:7]
	v_or_b32_e32 v96, s0, v50
	v_mov_b64_e32 v[94:95], s[16:17]
	v_mad_u64_u32 v[94:95], s[6:7], v96, s83, v[94:95]
	v_mad_i32_i24 v95, s1, v244, v95
	v_lshl_add_u64 v[94:95], v[94:95], 0, s[86:87]
	v_lshl_add_u64 v[94:95], v[38:39], 1, v[94:95]
	v_add_co_u32_e32 v98, vcc, s2, v94
	v_mov_b32_e32 v97, s1
	s_nop 0
	v_addc_co_u32_e32 v99, vcc, 0, v95, vcc
	flat_load_ushort v0, v[98:99] offset:512
	s_waitcnt lgkmcnt(0)
	flat_load_dword v61, v[72:73] offset:40
	v_lshlrev_b64 v[96:97], 12, v[96:97]
	v_lshl_add_u64 v[96:97], s[22:23], 0, v[96:97]
	s_waitcnt vmcnt(0)
	v_lshlrev_b32_e32 v0, 16, v0
	v_mul_f32_e32 v63, 0x3d372713, v0
	v_mul_f32_e32 v63, v63, v0
	v_fma_f32 v63, v63, v0, v0
	v_mul_f32_e32 v63, 0x3f4c422a, v63
	v_mul_f32_e32 v63, 0xc038aa3b, v63
	v_exp_f32_e32 v63, v63
	s_waitcnt lgkmcnt(0)
	v_add_f32_e32 v24, v24, v61
	v_add_f32_e32 v63, 1.0, v63
	v_rcp_f32_e32 v63, v63
	s_nop 0
	v_mul_f32_e32 v0, v63, v0
	v_mul_f32_e32 v0, v24, v0
	s_nop 1
	v_mov_b32_dpp v24, v0 quad_perm:[1,0,3,2] row_mask:0xf bank_mask:0xf
	s_and_saveexec_b64 s[6:7], s[4:5]
	s_cbranch_execz .LBB0_686
	s_waitcnt lgkmcnt(0)
	v_cvt_pk_bf16_f32 v0, v0, v24
	ds_write_b32 v208, v0 offset:1280
.LBB0_686:
	s_or_b64 exec, exec, s[6:7]
	s_waitcnt lgkmcnt(0)
	v_or_b32_e32 v24, s0, v52
	v_mov_b64_e32 v[98:99], s[16:17]
	v_mad_u64_u32 v[98:99], s[6:7], v24, s83, v[98:99]
	v_mad_i32_i24 v99, s1, v244, v99
	v_lshl_add_u64 v[98:99], v[98:99], 0, s[86:87]
	v_lshl_add_u64 v[98:99], v[38:39], 1, v[98:99]
	v_add_co_u32_e32 v100, vcc, s2, v98
	s_nop 1
	v_addc_co_u32_e32 v101, vcc, 0, v99, vcc
	flat_load_ushort v0, v[100:101] offset:512
	flat_load_dword v61, v[72:73] offset:44
	s_waitcnt vmcnt(0) lgkmcnt(0)
	v_lshlrev_b32_e32 v0, 16, v0
	v_mul_f32_e32 v63, 0x3d372713, v0
	v_mul_f32_e32 v63, v63, v0
	v_fma_f32 v63, v63, v0, v0
	v_mul_f32_e32 v63, 0x3f4c422a, v63
	v_mul_f32_e32 v63, 0xc038aa3b, v63
	v_exp_f32_e32 v63, v63
	v_add_f32_e32 v25, v25, v61
	v_add_f32_e32 v63, 1.0, v63
	v_rcp_f32_e32 v63, v63
	s_nop 0
	v_mul_f32_e32 v0, v63, v0
	v_mul_f32_e32 v0, v25, v0
	ds_bpermute_b32 v61, v43, v0
	v_mov_b32_e32 v25, s1
	v_lshlrev_b64 v[24:25], 12, v[24:25]
	v_lshl_add_u64 v[24:25], s[22:23], 0, v[24:25]
	s_and_saveexec_b64 s[6:7], s[4:5]
	s_cbranch_execz .LBB0_688
	s_waitcnt lgkmcnt(0)
	v_cvt_pk_bf16_f32 v0, v0, v61
	ds_write_b32 v208, v0 offset:1408
.LBB0_688:
	s_or_b64 exec, exec, s[6:7]
	v_or_b32_e32 v102, s0, v54
	v_mov_b64_e32 v[100:101], s[16:17]
	v_mad_u64_u32 v[100:101], s[6:7], v102, s83, v[100:101]
	v_mad_i32_i24 v101, s1, v244, v101
	v_lshl_add_u64 v[100:101], v[100:101], 0, s[86:87]
	v_lshl_add_u64 v[100:101], v[38:39], 1, v[100:101]
	v_add_co_u32_e32 v104, vcc, s2, v100
	v_mov_b32_e32 v103, s1
	s_nop 0
	v_addc_co_u32_e32 v105, vcc, 0, v101, vcc
	flat_load_ushort v0, v[104:105] offset:512
	s_waitcnt lgkmcnt(0)
	flat_load_dword v61, v[72:73] offset:64
	v_lshlrev_b64 v[102:103], 12, v[102:103]
	v_lshl_add_u64 v[102:103], s[22:23], 0, v[102:103]
	s_waitcnt vmcnt(0)
	v_lshlrev_b32_e32 v0, 16, v0
	v_mul_f32_e32 v63, 0x3d372713, v0
	v_mul_f32_e32 v63, v63, v0
	v_fma_f32 v63, v63, v0, v0
	v_mul_f32_e32 v63, 0x3f4c422a, v63
	v_mul_f32_e32 v63, 0xc038aa3b, v63
	v_exp_f32_e32 v63, v63
	s_waitcnt lgkmcnt(0)
	v_add_f32_e32 v26, v26, v61
	v_add_f32_e32 v63, 1.0, v63
	v_rcp_f32_e32 v63, v63
	s_nop 0
	v_mul_f32_e32 v0, v63, v0
	v_mul_f32_e32 v0, v26, v0
	s_nop 1
	v_mov_b32_dpp v26, v0 quad_perm:[1,0,3,2] row_mask:0xf bank_mask:0xf
	s_and_saveexec_b64 s[6:7], s[4:5]
	s_cbranch_execz .LBB0_690
	s_waitcnt lgkmcnt(0)
	v_cvt_pk_bf16_f32 v0, v0, v26
	ds_write_b32 v208, v0 offset:2048
; __device__ __forceinline__ float bf2f(unsigned short h) { return __uint_as_float(((unsigned)h) << 16); }
; __device__ __forceinline__ unsigned cvtpk(float lo, float hi) { unsigned r; asm volatile("v_cvt_pk_bf16_f32 %0, %1, %2" : "=v"(r) : "v"(lo), "v"(hi)); return r; }
; __device__ __forceinline__ int crow(int r, int hi) { return (r & 3) + 8 * (r >> 2) + 4 * hi; }
; __device__ __forceinline__ void ph_misc(const Args& a, char* lds, int l) {
;     ...
;         for (int ci = 0; ci < 2; ++ci)
; #pragma unroll
;             for (int r = 0; r < 16; ++r) { const int t = 32 * tb + crow(r, hi), c = 32 * (cb0 + ci) + r32; const size_t row = row0 + t;
;                 const float uval = gelu_tanh(bf2f(P[row * NIN + PC_U + g * 128 + c])); const float val = uval * (acc[ci][r] + b_s[l * 512 + g * 128 + t]);
;                 const float vn = __shfl_xor(val, 1); if ((r32 & 1) == 0) *(unsigned*)(MIX + row * DM + 1024 + g * 128 + c) = cvtpk(val, vn); }
.LBB0_690:
	s_or_b64 exec, exec, s[6:7]
	s_waitcnt lgkmcnt(0)
	v_or_b32_e32 v26, s0, v56
	v_mov_b64_e32 v[104:105], s[16:17]
	v_mad_u64_u32 v[104:105], s[6:7], v26, s83, v[104:105]
	v_mad_i32_i24 v105, s1, v244, v105
	v_lshl_add_u64 v[104:105], v[104:105], 0, s[86:87]
	v_lshl_add_u64 v[104:105], v[38:39], 1, v[104:105]
	v_add_co_u32_e32 v106, vcc, s2, v104
	s_nop 1
	v_addc_co_u32_e32 v107, vcc, 0, v105, vcc
	flat_load_ushort v0, v[106:107] offset:512
	flat_load_dword v61, v[72:73] offset:68
	s_waitcnt vmcnt(0) lgkmcnt(0)
	v_lshlrev_b32_e32 v0, 16, v0
	v_mul_f32_e32 v63, 0x3d372713, v0
	v_mul_f32_e32 v63, v63, v0
	v_fma_f32 v63, v63, v0, v0
	v_mul_f32_e32 v63, 0x3f4c422a, v63
	v_mul_f32_e32 v63, 0xc038aa3b, v63
	v_exp_f32_e32 v63, v63
	v_add_f32_e32 v27, v27, v61
	v_add_f32_e32 v63, 1.0, v63
	v_rcp_f32_e32 v63, v63
	s_nop 0
	v_mul_f32_e32 v0, v63, v0
	v_mul_f32_e32 v0, v27, v0
	ds_bpermute_b32 v61, v43, v0
	v_mov_b32_e32 v27, s1
	v_lshlrev_b64 v[26:27], 12, v[26:27]
	v_lshl_add_u64 v[26:27], s[22:23], 0, v[26:27]
	s_and_saveexec_b64 s[6:7], s[4:5]
	s_cbranch_execz .LBB0_692
	s_waitcnt lgkmcnt(0)
	v_cvt_pk_bf16_f32 v0, v0, v61
	ds_write_b32 v208, v0 offset:2176
.LBB0_692:
	s_or_b64 exec, exec, s[6:7]
	v_or_b32_e32 v108, s0, v58
	v_mov_b64_e32 v[106:107], s[16:17]
	v_mad_u64_u32 v[106:107], s[6:7], v108, s83, v[106:107]
	v_mad_i32_i24 v107, s1, v244, v107
	v_lshl_add_u64 v[106:107], v[106:107], 0, s[86:87]
	v_lshl_add_u64 v[106:107], v[38:39], 1, v[106:107]
	v_add_co_u32_e32 v110, vcc, s2, v106
	v_mov_b32_e32 v109, s1
	s_nop 0
	v_addc_co_u32_e32 v111, vcc, 0, v107, vcc
	flat_load_ushort v0, v[110:111] offset:512
	s_waitcnt lgkmcnt(0)
	flat_load_dword v61, v[72:73] offset:72
	v_lshlrev_b64 v[108:109], 12, v[108:109]
	v_lshl_add_u64 v[108:109], s[22:23], 0, v[108:109]
	s_waitcnt vmcnt(0)
	v_lshlrev_b32_e32 v0, 16, v0
	v_mul_f32_e32 v63, 0x3d372713, v0
	v_mul_f32_e32 v63, v63, v0
	v_fma_f32 v63, v63, v0, v0
	v_mul_f32_e32 v63, 0x3f4c422a, v63
	v_mul_f32_e32 v63, 0xc038aa3b, v63
	v_exp_f32_e32 v63, v63
	s_waitcnt lgkmcnt(0)
	v_add_f32_e32 v28, v28, v61
	v_add_f32_e32 v63, 1.0, v63
	v_rcp_f32_e32 v63, v63
	s_nop 0
	v_mul_f32_e32 v0, v63, v0
	v_mul_f32_e32 v0, v28, v0
	s_nop 1
	v_mov_b32_dpp v28, v0 quad_perm:[1,0,3,2] row_mask:0xf bank_mask:0xf
	s_and_saveexec_b64 s[6:7], s[4:5]
	s_cbranch_execz .LBB0_694
	s_waitcnt lgkmcnt(0)
	v_cvt_pk_bf16_f32 v0, v0, v28
	ds_write_b32 v208, v0 offset:2304
.LBB0_694:
	s_or_b64 exec, exec, s[6:7]
	s_waitcnt lgkmcnt(0)
	v_or_b32_e32 v28, s0, v60
	v_mov_b64_e32 v[110:111], s[16:17]
	v_mad_u64_u32 v[110:111], s[6:7], v28, s83, v[110:111]
	v_mad_i32_i24 v111, s1, v244, v111
	v_lshl_add_u64 v[110:111], v[110:111], 0, s[86:87]
	v_lshl_add_u64 v[110:111], v[38:39], 1, v[110:111]
	v_add_co_u32_e32 v112, vcc, s2, v110
	s_nop 1
	v_addc_co_u32_e32 v113, vcc, 0, v111, vcc
	flat_load_ushort v0, v[112:113] offset:512
	flat_load_dword v61, v[72:73] offset:76
	s_waitcnt vmcnt(0) lgkmcnt(0)
	v_lshlrev_b32_e32 v0, 16, v0
	v_mul_f32_e32 v63, 0x3d372713, v0
	v_mul_f32_e32 v63, v63, v0
	v_fma_f32 v63, v63, v0, v0
	v_mul_f32_e32 v63, 0x3f4c422a, v63
	v_mul_f32_e32 v63, 0xc038aa3b, v63
	v_exp_f32_e32 v63, v63
	v_add_f32_e32 v29, v29, v61
	v_add_f32_e32 v63, 1.0, v63
	v_rcp_f32_e32 v63, v63
	s_nop 0
	v_mul_f32_e32 v0, v63, v0
	v_mul_f32_e32 v0, v29, v0
	ds_bpermute_b32 v61, v43, v0
	v_mov_b32_e32 v29, s1
	v_lshlrev_b64 v[28:29], 12, v[28:29]
	v_lshl_add_u64 v[28:29], s[22:23], 0, v[28:29]
	s_and_saveexec_b64 s[6:7], s[4:5]
	s_cbranch_execz .LBB0_696
	s_waitcnt lgkmcnt(0)
	v_cvt_pk_bf16_f32 v0, v0, v61
	ds_write_b32 v208, v0 offset:2432
.LBB0_696:
	s_or_b64 exec, exec, s[6:7]
	v_or_b32_e32 v114, s0, v62
	v_mov_b64_e32 v[112:113], s[16:17]
	v_mad_u64_u32 v[112:113], s[6:7], v114, s83, v[112:113]
	v_mad_i32_i24 v113, s1, v244, v113
	v_lshl_add_u64 v[112:113], v[112:113], 0, s[86:87]
	v_lshl_add_u64 v[112:113], v[38:39], 1, v[112:113]
	v_add_co_u32_e32 v116, vcc, s2, v112
	v_mov_b32_e32 v115, s1
	s_nop 0
	v_addc_co_u32_e32 v117, vcc, 0, v113, vcc
	flat_load_ushort v0, v[116:117] offset:512
	s_waitcnt lgkmcnt(0)
	flat_load_dword v61, v[72:73] offset:96
	v_lshlrev_b64 v[114:115], 12, v[114:115]
	v_lshl_add_u64 v[114:115], s[22:23], 0, v[114:115]
	s_waitcnt vmcnt(0)
	v_lshlrev_b32_e32 v0, 16, v0
	v_mul_f32_e32 v63, 0x3d372713, v0
	v_mul_f32_e32 v63, v63, v0
	v_fma_f32 v63, v63, v0, v0
	v_mul_f32_e32 v63, 0x3f4c422a, v63
	v_mul_f32_e32 v63, 0xc038aa3b, v63
	v_exp_f32_e32 v63, v63
	s_waitcnt lgkmcnt(0)
	v_add_f32_e32 v30, v30, v61
	v_add_f32_e32 v63, 1.0, v63
	v_rcp_f32_e32 v63, v63
	s_nop 0
	v_mul_f32_e32 v0, v63, v0
	v_mul_f32_e32 v0, v30, v0
	s_nop 1
	v_mov_b32_dpp v30, v0 quad_perm:[1,0,3,2] row_mask:0xf bank_mask:0xf
	s_and_saveexec_b64 s[6:7], s[4:5]
	s_cbranch_execz .LBB0_698
	s_waitcnt lgkmcnt(0)
	v_cvt_pk_bf16_f32 v0, v0, v30
	ds_write_b32 v208, v0 offset:3072
; __device__ __forceinline__ float bf2f(unsigned short h) { return __uint_as_float(((unsigned)h) << 16); }
; __device__ __forceinline__ unsigned cvtpk(float lo, float hi) { unsigned r; asm volatile("v_cvt_pk_bf16_f32 %0, %1, %2" : "=v"(r) : "v"(lo), "v"(hi)); return r; }
; __device__ __forceinline__ int crow(int r, int hi) { return (r & 3) + 8 * (r >> 2) + 4 * hi; }
; __device__ __forceinline__ void ph_misc(const Args& a, char* lds, int l) {
;     ...
;         for (int ci = 0; ci < 2; ++ci)
; #pragma unroll
;             for (int r = 0; r < 16; ++r) { const int t = 32 * tb + crow(r, hi), c = 32 * (cb0 + ci) + r32; const size_t row = row0 + t;
;                 const float uval = gelu_tanh(bf2f(P[row * NIN + PC_U + g * 128 + c])); const float val = uval * (acc[ci][r] + b_s[l * 512 + g * 128 + t]);
;                 const float vn = __shfl_xor(val, 1); if ((r32 & 1) == 0) *(unsigned*)(MIX + row * DM + 1024 + g * 128 + c) = cvtpk(val, vn); }
.LBB0_698:
	s_or_b64 exec, exec, s[6:7]
	s_waitcnt lgkmcnt(0)
	v_or_b32_e32 v30, s0, v64
	v_mov_b64_e32 v[116:117], s[16:17]
	v_mad_u64_u32 v[116:117], s[6:7], v30, s83, v[116:117]
	v_mad_i32_i24 v117, s1, v244, v117
	v_lshl_add_u64 v[116:117], v[116:117], 0, s[86:87]
	v_lshl_add_u64 v[116:117], v[38:39], 1, v[116:117]
	v_add_co_u32_e32 v118, vcc, s2, v116
	s_nop 1
	v_addc_co_u32_e32 v119, vcc, 0, v117, vcc
	flat_load_ushort v0, v[118:119] offset:512
	flat_load_dword v61, v[72:73] offset:100
	s_waitcnt vmcnt(0) lgkmcnt(0)
	v_lshlrev_b32_e32 v0, 16, v0
	v_mul_f32_e32 v63, 0x3d372713, v0
	v_mul_f32_e32 v63, v63, v0
	v_fma_f32 v63, v63, v0, v0
	v_mul_f32_e32 v63, 0x3f4c422a, v63
	v_mul_f32_e32 v63, 0xc038aa3b, v63
	v_exp_f32_e32 v63, v63
	v_add_f32_e32 v31, v31, v61
	v_add_f32_e32 v63, 1.0, v63
	v_rcp_f32_e32 v63, v63
	s_nop 0
	v_mul_f32_e32 v0, v63, v0
	v_mul_f32_e32 v0, v31, v0
	ds_bpermute_b32 v61, v43, v0
	v_mov_b32_e32 v31, s1
	v_lshlrev_b64 v[30:31], 12, v[30:31]
	v_lshl_add_u64 v[30:31], s[22:23], 0, v[30:31]
	s_and_saveexec_b64 s[6:7], s[4:5]
	s_cbranch_execz .LBB0_700
	s_waitcnt lgkmcnt(0)
	v_cvt_pk_bf16_f32 v0, v0, v61
	ds_write_b32 v208, v0 offset:3200
.LBB0_700:
	s_or_b64 exec, exec, s[6:7]
	v_or_b32_e32 v120, s0, v66
	v_mov_b64_e32 v[118:119], s[16:17]
	v_mad_u64_u32 v[118:119], s[6:7], v120, s83, v[118:119]
	v_mad_i32_i24 v119, s1, v244, v119
	v_lshl_add_u64 v[118:119], v[118:119], 0, s[86:87]
	v_lshl_add_u64 v[118:119], v[38:39], 1, v[118:119]
	v_add_co_u32_e32 v122, vcc, s2, v118
	v_mov_b32_e32 v121, s1
	s_nop 0
	v_addc_co_u32_e32 v123, vcc, 0, v119, vcc
	flat_load_ushort v0, v[122:123] offset:512
	s_waitcnt lgkmcnt(0)
	flat_load_dword v61, v[72:73] offset:104
	v_lshlrev_b64 v[120:121], 12, v[120:121]
	v_lshl_add_u64 v[120:121], s[22:23], 0, v[120:121]
	s_waitcnt vmcnt(0)
	v_lshlrev_b32_e32 v0, 16, v0
	v_mul_f32_e32 v63, 0x3d372713, v0
	v_mul_f32_e32 v63, v63, v0
	v_fma_f32 v63, v63, v0, v0
	v_mul_f32_e32 v63, 0x3f4c422a, v63
	v_mul_f32_e32 v63, 0xc038aa3b, v63
	v_exp_f32_e32 v63, v63
	s_waitcnt lgkmcnt(0)
	v_add_f32_e32 v32, v32, v61
	v_add_f32_e32 v63, 1.0, v63
	v_rcp_f32_e32 v63, v63
	s_nop 0
	v_mul_f32_e32 v0, v63, v0
	v_mul_f32_e32 v0, v32, v0
	s_nop 1
	v_mov_b32_dpp v32, v0 quad_perm:[1,0,3,2] row_mask:0xf bank_mask:0xf
	s_and_saveexec_b64 s[6:7], s[4:5]
	s_cbranch_execz .LBB0_702
	s_waitcnt lgkmcnt(0)
	v_cvt_pk_bf16_f32 v0, v0, v32
	ds_write_b32 v208, v0 offset:3328
.LBB0_702:
	s_or_b64 exec, exec, s[6:7]
	s_waitcnt lgkmcnt(0)
	v_or_b32_e32 v32, s0, v68
	v_mov_b64_e32 v[122:123], s[16:17]
	v_mad_u64_u32 v[122:123], s[6:7], v32, s83, v[122:123]
	v_mad_i32_i24 v123, s1, v244, v123
	v_lshl_add_u64 v[122:123], v[122:123], 0, s[86:87]
	v_lshl_add_u64 v[122:123], v[38:39], 1, v[122:123]
	s_movk_i32 s0, 0x1000
	v_add_co_u32_e32 v124, vcc, s0, v122
	s_nop 1
	v_addc_co_u32_e32 v125, vcc, 0, v123, vcc
	flat_load_ushort v0, v[124:125] offset:512
	flat_load_dword v61, v[72:73] offset:108
	s_waitcnt vmcnt(0) lgkmcnt(0)
	v_lshlrev_b32_e32 v0, 16, v0
	v_mul_f32_e32 v63, 0x3d372713, v0
	v_mul_f32_e32 v63, v63, v0
	v_fma_f32 v63, v63, v0, v0
	v_mul_f32_e32 v63, 0x3f4c422a, v63
	v_mul_f32_e32 v63, 0xc038aa3b, v63
	v_exp_f32_e32 v63, v63
	v_add_f32_e32 v33, v33, v61
	v_add_f32_e32 v63, 1.0, v63
	v_rcp_f32_e32 v63, v63
	s_nop 0
	v_mul_f32_e32 v0, v63, v0
	v_mul_f32_e32 v0, v33, v0
	ds_bpermute_b32 v61, v43, v0
	v_mov_b32_e32 v33, s1
	v_lshlrev_b64 v[32:33], 12, v[32:33]
	v_lshl_add_u64 v[32:33], s[22:23], 0, v[32:33]
	s_and_saveexec_b64 s[0:1], s[4:5]
	s_cbranch_execz .LBB0_704
	s_waitcnt lgkmcnt(0)
	v_cvt_pk_bf16_f32 v0, v0, v61
	ds_write_b32 v208, v0 offset:3456
.LBB0_704:
	s_or_b64 exec, exec, s[0:1]
	s_mov_b64 s[0:1], 0x1200
	v_lshl_add_u64 v[74:75], v[74:75], 0, s[0:1]
	flat_load_ushort v0, v[74:75] offset:64
	s_waitcnt lgkmcnt(0)
	flat_load_dword v61, v[78:79]
	s_waitcnt vmcnt(0)
	v_lshlrev_b32_e32 v0, 16, v0
	v_mul_f32_e32 v63, 0x3d372713, v0
	v_mul_f32_e32 v63, v63, v0
	v_fma_f32 v63, v63, v0, v0
	v_mul_f32_e32 v63, 0x3f4c422a, v63
	v_mul_f32_e32 v63, 0xc038aa3b, v63
	v_exp_f32_e32 v63, v63
	s_waitcnt lgkmcnt(0)
	v_add_f32_e32 v2, v2, v61
	v_add_f32_e32 v63, 1.0, v63
	v_rcp_f32_e32 v63, v63
	s_nop 0
	v_mul_f32_e32 v0, v63, v0
	v_mul_f32_e32 v0, v2, v0
	s_nop 1
	v_mov_b32_dpp v2, v0 quad_perm:[1,0,3,2] row_mask:0xf bank_mask:0xf
	s_and_saveexec_b64 s[0:1], s[4:5]
	s_cbranch_execz .LBB0_706
	s_waitcnt lgkmcnt(0)
	v_cvt_pk_bf16_f32 v0, v0, v2
	ds_write_b32 v208, v0 offset:64
